# loop-edge edit in expert_dots inner loop: next head's address VALU hoisted into tail DPP chain nop slots (on v23)
# baseline (speedup 1.0000x reference)
; DI void expert_dots(const Params& p, int nrows, char* smem) {
;     ...
;       for (int base = cb; base < nend; base += 8) {
;         const int k0 = base + g, k1 = base + 4 + g;
;         const u32 ent0 = list[min(k0, n - 1)], ent1 = list[min(k1, n - 1)];
;         const unsigned char* ur0 = PU + (size_t)(ent0 & 0xffffu) * D;
;         const unsigned char* ur1 = PU + (size_t)(ent1 & 0xffffu) * D;
;         int4 ua[4], ub[4];
;         ua[0] = *(const int4*)(ur0); ua[1] = *(const int4*)(ur0 + 256); ua[2] = *(const int4*)(ur0 + 512); ua[3] = *(const int4*)(ur0 + 768);
;         ub[0] = *(const int4*)(ur1); ub[1] = *(const int4*)(ur1 + 256); ub[2] = *(const int4*)(ur1 + 512); ub[3] = *(const int4*)(ur1 + 768);
.Ldp_A:
	s_add_i32 s33, s33, 8
	s_cmp_ge_u32 s33, s1
	s_cbranch_scc1 .Ldp_A_last
	v_add_u32_e32 v186, s33, v106
	v_add_u32_e32 v187, 4, v186
	v_min_i32_e32 v186, s5, v186
	v_min_i32_e32 v187, s5, v187
	v_lshl_add_u32 v186, v186, 2, v108
	v_lshl_add_u32 v187, v187, 2, v108
.Ldp_A2:
	ds_read_b32 v155, v186
	ds_read_b32 v156, v187
	s_waitcnt lgkmcnt(1)
	v_lshlrev_b32_e32 v155, 10, v155
	v_and_b32_e32 v196, 0x3fffc00, v155
	s_waitcnt lgkmcnt(0)
	v_lshlrev_b32_e32 v155, 10, v156
	v_lshl_add_u64 v[168:169], v[64:65], 0, v[196:197]
	v_and_b32_e32 v196, 0x3fffc00, v155
	v_lshl_add_u64 v[184:185], v[64:65], 0, v[196:197]
	global_load_dwordx4 v[156:159], v[168:169], off
	global_load_dwordx4 v[160:163], v[168:169], off offset:256
	global_load_dwordx4 v[164:167], v[168:169], off offset:512
	s_nop 0
	global_load_dwordx4 v[168:171], v[168:169], off offset:768
	s_nop 0
	global_load_dwordx4 v[172:175], v[184:185], off
	global_load_dwordx4 v[176:179], v[184:185], off offset:256
	global_load_dwordx4 v[180:183], v[184:185], off offset:512
	s_nop 0
	global_load_dwordx4 v[184:187], v[184:185], off offset:768
	s_waitcnt vmcnt(8)
	s_branch .Ldp_A_comp

; DI void expert_dots(const Params& p, int nrows, char* smem) {
;     ...
;   auto dot_row = [&](const int4 (&uu)[4], const f2 (&hf)[32]) {
;     const int uw[16] = {uu[0].x, uu[0].y, uu[0].z, uu[0].w, uu[1].x, uu[1].y, uu[1].z, uu[1].w,
;                         uu[2].x, uu[2].y, uu[2].z, uu[2].w, uu[3].x, uu[3].y, uu[3].z, uu[3].w};
;     f2 acc = {0.f, 0.f}, acc2 = {0.f, 0.f};
; #pragma unroll
;     for (int j = 0; j < 16; j++) {
;       acc = __builtin_elementwise_fma(__builtin_amdgcn_cvt_pk_f32_fp8(uw[j], false), hf[2 * j], acc);
;       acc2 = __builtin_elementwise_fma(__builtin_amdgcn_cvt_pk_f32_fp8(uw[j], true), hf[2 * j + 1], acc2);
;     }
;     return row16_sum((acc.x + acc.y) + (acc2.x + acc2.y));
;   };
;     ...
;         const float d0 = dot_row(ua, hf);
;         const float d1 = dot_row(ub, hf);
;         const int it0 = (base - cb) >> 2;
;         dk = (s == it0) ? d0 : dk;
.Ldp_A_comp:
	v_cmp_eq_u32_e32 vcc, 0, v114
	s_nop 0
	v_cvt_pk_f32_fp8_sdwa v[150:151], v116 src0_sel:WORD_1
	v_cvt_pk_f32_fp8_e32 v[148:149], v116
	v_cvt_pk_f32_fp8_e32 v[152:153], v117
	v_cvt_pk_f32_fp8_sdwa v[116:117], v117 src0_sel:WORD_1
	v_pk_fma_f32 v[150:151], v[150:151], v[48:49], 0 op_sel_hi:[1,1,0]
	v_pk_fma_f32 v[148:149], v[148:149], v[72:73], 0 op_sel_hi:[1,1,0]
	v_pk_fma_f32 v[116:117], v[116:117], v[50:51], v[150:151]
	v_cvt_pk_f32_fp8_e32 v[150:151], v118
	v_pk_fma_f32 v[148:149], v[152:153], v[74:75], v[148:149]
	s_nop 0
	v_pk_fma_f32 v[148:149], v[150:151], v[76:77], v[148:149]
	v_cvt_pk_f32_fp8_sdwa v[150:151], v118 src0_sel:WORD_1
	v_pk_fma_f32 v[116:117], v[150:151], v[32:33], v[116:117]
	v_cvt_pk_f32_fp8_e32 v[150:151], v119
	v_cvt_pk_f32_fp8_sdwa v[118:119], v119 src0_sel:WORD_1
	v_pk_fma_f32 v[148:149], v[150:151], v[78:79], v[148:149]
	v_pk_fma_f32 v[116:117], v[118:119], v[34:35], v[116:117]
	s_nop 0
	v_cvt_pk_f32_fp8_e32 v[118:119], v120
	v_pk_fma_f32 v[118:119], v[118:119], v[80:81], v[148:149]
	v_cvt_pk_f32_fp8_sdwa v[148:149], v120 src0_sel:WORD_1
	v_pk_fma_f32 v[116:117], v[148:149], v[52:53], v[116:117]
	v_cvt_pk_f32_fp8_e32 v[148:149], v121
	v_cvt_pk_f32_fp8_sdwa v[120:121], v121 src0_sel:WORD_1
	v_pk_fma_f32 v[118:119], v[148:149], v[82:83], v[118:119]
	v_pk_fma_f32 v[116:117], v[120:121], v[54:55], v[116:117]
	v_cvt_pk_f32_fp8_e32 v[120:121], v122
	v_pk_fma_f32 v[118:119], v[120:121], v[84:85], v[118:119]
	v_cvt_pk_f32_fp8_sdwa v[120:121], v122 src0_sel:WORD_1
	v_pk_fma_f32 v[116:117], v[120:121], v[36:37], v[116:117]
	v_cvt_pk_f32_fp8_e32 v[120:121], v123
	v_pk_fma_f32 v[118:119], v[120:121], v[86:87], v[118:119]
	v_cvt_pk_f32_fp8_sdwa v[120:121], v123 src0_sel:WORD_1
	v_pk_fma_f32 v[116:117], v[120:121], v[38:39], v[116:117]
	s_nop 0
	v_cvt_pk_f32_fp8_e32 v[120:121], v124
	v_pk_fma_f32 v[118:119], v[120:121], v[88:89], v[118:119]
	v_cvt_pk_f32_fp8_sdwa v[120:121], v124 src0_sel:WORD_1
	v_pk_fma_f32 v[116:117], v[120:121], v[56:57], v[116:117]
	v_cvt_pk_f32_fp8_e32 v[120:121], v125
	v_pk_fma_f32 v[118:119], v[120:121], v[90:91], v[118:119]
	v_cvt_pk_f32_fp8_sdwa v[120:121], v125 src0_sel:WORD_1
	v_pk_fma_f32 v[116:117], v[120:121], v[58:59], v[116:117]
	v_cvt_pk_f32_fp8_e32 v[120:121], v126
	v_pk_fma_f32 v[118:119], v[120:121], v[92:93], v[118:119]
	v_cvt_pk_f32_fp8_sdwa v[120:121], v126 src0_sel:WORD_1
	v_pk_fma_f32 v[116:117], v[120:121], v[40:41], v[116:117]
	v_cvt_pk_f32_fp8_e32 v[120:121], v127
	v_pk_fma_f32 v[118:119], v[120:121], v[94:95], v[118:119]
	v_cvt_pk_f32_fp8_sdwa v[120:121], v127 src0_sel:WORD_1
	v_pk_fma_f32 v[116:117], v[120:121], v[42:43], v[116:117]
	s_nop 0
	v_cvt_pk_f32_fp8_e32 v[120:121], v128
	v_pk_fma_f32 v[118:119], v[120:121], v[96:97], v[118:119]
	v_cvt_pk_f32_fp8_sdwa v[120:121], v128 src0_sel:WORD_1
	v_pk_fma_f32 v[116:117], v[120:121], v[60:61], v[116:117]
	v_cvt_pk_f32_fp8_e32 v[120:121], v129
	v_pk_fma_f32 v[118:119], v[120:121], v[98:99], v[118:119]
	v_cvt_pk_f32_fp8_sdwa v[120:121], v129 src0_sel:WORD_1
	v_pk_fma_f32 v[116:117], v[120:121], v[62:63], v[116:117]
	v_cvt_pk_f32_fp8_e32 v[120:121], v130
	v_pk_fma_f32 v[118:119], v[120:121], v[100:101], v[118:119]
	v_cvt_pk_f32_fp8_sdwa v[120:121], v130 src0_sel:WORD_1
	v_pk_fma_f32 v[116:117], v[120:121], v[44:45], v[116:117]
	v_cvt_pk_f32_fp8_e32 v[120:121], v131
	v_pk_fma_f32 v[118:119], v[120:121], v[102:103], v[118:119]
	v_cvt_pk_f32_fp8_sdwa v[120:121], v131 src0_sel:WORD_1
	v_pk_fma_f32 v[116:117], v[120:121], v[46:47], v[116:117]
	v_mov_b32_e32 v120, v118
	v_mov_b32_e32 v121, v116
	v_mov_b32_e32 v116, v119
	v_pk_add_f32 v[116:117], v[120:121], v[116:117]
	s_nop 0
	v_cvt_pk_f32_fp8_e32 v[120:121], v133
	v_add_f32_e32 v115, v116, v117
	v_cvt_pk_f32_fp8_e32 v[116:117], v132
	v_cvt_pk_f32_fp8_sdwa v[118:119], v132 src0_sel:WORD_1
	v_add_f32_dpp v115, v115, v115 row_ror:8 row_mask:0xf bank_mask:0xf bound_ctrl:1
	v_pk_fma_f32 v[116:117], v[116:117], v[72:73], 0 op_sel_hi:[1,1,0]
	s_nop 0
	v_pk_fma_f32 v[116:117], v[120:121], v[74:75], v[116:117]
	v_cvt_pk_f32_fp8_sdwa v[120:121], v133 src0_sel:WORD_1
	v_pk_fma_f32 v[118:119], v[118:119], v[48:49], 0 op_sel_hi:[1,1,0]
	v_add_f32_dpp v115, v115, v115 row_ror:4 row_mask:0xf bank_mask:0xf bound_ctrl:1
	v_pk_fma_f32 v[118:119], v[120:121], v[50:51], v[118:119]
	v_cvt_pk_f32_fp8_e32 v[120:121], v134
	v_add_f32_dpp v115, v115, v115 row_ror:2 row_mask:0xf bank_mask:0xf bound_ctrl:1
	v_pk_fma_f32 v[116:117], v[120:121], v[76:77], v[116:117]
	v_cvt_pk_f32_fp8_sdwa v[120:121], v134 src0_sel:WORD_1
	v_add_f32_dpp v115, v115, v115 row_ror:1 row_mask:0xf bank_mask:0xf bound_ctrl:1
	v_cndmask_b32_e32 v113, v113, v115, vcc
; DI void expert_dots(const Params& p, int nrows, char* smem) {
;     ...
;       for (int base = cb; base < nend; base += 8) {
;         const int k0 = base + g, k1 = base + 4 + g;
;         const u32 ent0 = list[min(k0, n - 1)], ent1 = list[min(k1, n - 1)];
;         const unsigned char* ur0 = PU + (size_t)(ent0 & 0xffffu) * D;
;         const unsigned char* ur1 = PU + (size_t)(ent1 & 0xffffu) * D;
;         int4 ua[4], ub[4];
;         ua[0] = *(const int4*)(ur0); ua[1] = *(const int4*)(ur0 + 256); ua[2] = *(const int4*)(ur0 + 512); ua[3] = *(const int4*)(ur0 + 768);
;         ub[0] = *(const int4*)(ur1); ub[1] = *(const int4*)(ur1 + 256); ub[2] = *(const int4*)(ur1 + 512); ub[3] = *(const int4*)(ur1 + 768);
;         const float d0 = dot_row(ua, hf);
;         const float d1 = dot_row(ub, hf);
;         const int it0 = (base - cb) >> 2;
;         dk = (s == it0) ? d0 : dk;
;         dk = (s == it0 + 1) ? d1 : dk;
	v_cmp_eq_u32_e32 vcc, 1, v114
	v_pk_fma_f32 v[118:119], v[120:121], v[32:33], v[118:119]
	v_cvt_pk_f32_fp8_e32 v[120:121], v135
	v_add_u32_e32 v114, -2, v114
	v_pk_fma_f32 v[116:117], v[120:121], v[78:79], v[116:117]
	v_cvt_pk_f32_fp8_sdwa v[120:121], v135 src0_sel:WORD_1
	v_pk_fma_f32 v[118:119], v[120:121], v[34:35], v[118:119]
	s_nop 0
	v_cvt_pk_f32_fp8_e32 v[120:121], v136
	v_pk_fma_f32 v[116:117], v[120:121], v[80:81], v[116:117]
	v_cvt_pk_f32_fp8_sdwa v[120:121], v136 src0_sel:WORD_1
	v_pk_fma_f32 v[118:119], v[120:121], v[52:53], v[118:119]
	v_cvt_pk_f32_fp8_e32 v[120:121], v137
	v_pk_fma_f32 v[116:117], v[120:121], v[82:83], v[116:117]
	v_cvt_pk_f32_fp8_sdwa v[120:121], v137 src0_sel:WORD_1
	v_pk_fma_f32 v[118:119], v[120:121], v[54:55], v[118:119]
	v_cvt_pk_f32_fp8_e32 v[120:121], v138
	v_pk_fma_f32 v[116:117], v[120:121], v[84:85], v[116:117]
	v_cvt_pk_f32_fp8_sdwa v[120:121], v138 src0_sel:WORD_1
	v_pk_fma_f32 v[118:119], v[120:121], v[36:37], v[118:119]
	v_cvt_pk_f32_fp8_e32 v[120:121], v139
	v_pk_fma_f32 v[116:117], v[120:121], v[86:87], v[116:117]
	v_cvt_pk_f32_fp8_sdwa v[120:121], v139 src0_sel:WORD_1
	v_pk_fma_f32 v[118:119], v[120:121], v[38:39], v[118:119]
	s_nop 0
	v_cvt_pk_f32_fp8_e32 v[120:121], v140
	v_pk_fma_f32 v[116:117], v[120:121], v[88:89], v[116:117]
	v_cvt_pk_f32_fp8_sdwa v[120:121], v140 src0_sel:WORD_1
	v_pk_fma_f32 v[118:119], v[120:121], v[56:57], v[118:119]
	v_cvt_pk_f32_fp8_e32 v[120:121], v141
	v_pk_fma_f32 v[116:117], v[120:121], v[90:91], v[116:117]
	v_cvt_pk_f32_fp8_sdwa v[120:121], v141 src0_sel:WORD_1
	v_pk_fma_f32 v[118:119], v[120:121], v[58:59], v[118:119]
	v_cvt_pk_f32_fp8_e32 v[120:121], v142
	v_pk_fma_f32 v[116:117], v[120:121], v[92:93], v[116:117]
	v_cvt_pk_f32_fp8_sdwa v[120:121], v142 src0_sel:WORD_1
	v_pk_fma_f32 v[118:119], v[120:121], v[40:41], v[118:119]
	v_cvt_pk_f32_fp8_e32 v[120:121], v143
	v_pk_fma_f32 v[116:117], v[120:121], v[94:95], v[116:117]
	v_cvt_pk_f32_fp8_sdwa v[120:121], v143 src0_sel:WORD_1
	v_pk_fma_f32 v[118:119], v[120:121], v[42:43], v[118:119]
	s_nop 0
	v_cvt_pk_f32_fp8_e32 v[120:121], v144
	v_pk_fma_f32 v[116:117], v[120:121], v[96:97], v[116:117]
	v_cvt_pk_f32_fp8_sdwa v[120:121], v144 src0_sel:WORD_1
	v_pk_fma_f32 v[118:119], v[120:121], v[60:61], v[118:119]
	v_cvt_pk_f32_fp8_e32 v[120:121], v145
	v_pk_fma_f32 v[116:117], v[120:121], v[98:99], v[116:117]
	v_cvt_pk_f32_fp8_sdwa v[120:121], v145 src0_sel:WORD_1
	v_pk_fma_f32 v[118:119], v[120:121], v[62:63], v[118:119]
	v_cvt_pk_f32_fp8_e32 v[120:121], v146
	v_pk_fma_f32 v[116:117], v[120:121], v[100:101], v[116:117]
	v_cvt_pk_f32_fp8_sdwa v[120:121], v146 src0_sel:WORD_1
	v_pk_fma_f32 v[118:119], v[120:121], v[44:45], v[118:119]
	v_cvt_pk_f32_fp8_e32 v[120:121], v147
	v_pk_fma_f32 v[116:117], v[120:121], v[102:103], v[116:117]
	v_cvt_pk_f32_fp8_sdwa v[120:121], v147 src0_sel:WORD_1
	v_pk_fma_f32 v[118:119], v[120:121], v[46:47], v[118:119]
	v_mov_b32_e32 v120, v116
	v_mov_b32_e32 v121, v118
	v_mov_b32_e32 v118, v117
	v_pk_add_f32 v[116:117], v[120:121], v[118:119]
	s_nop 0
	v_add_f32_e32 v116, v116, v117
	v_add3_u32 v146, s33, v106, 8
	v_add_u32_e32 v147, 4, v146
	v_add_f32_dpp v116, v116, v116 row_ror:8 row_mask:0xf bank_mask:0xf bound_ctrl:1
	v_min_i32_e32 v146, s5, v146
	v_min_i32_e32 v147, s5, v147
	v_add_f32_dpp v116, v116, v116 row_ror:4 row_mask:0xf bank_mask:0xf bound_ctrl:1
	v_lshl_add_u32 v146, v146, 2, v108
	v_lshl_add_u32 v147, v147, 2, v108
	v_add_f32_dpp v116, v116, v116 row_ror:2 row_mask:0xf bank_mask:0xf bound_ctrl:1
	s_nop 1
	v_add_f32_dpp v116, v116, v116 row_ror:1 row_mask:0xf bank_mask:0xf bound_ctrl:1
	v_cndmask_b32_e32 v113, v113, v116, vcc
	s_cbranch_scc1 .Ldp_done
.Ldp_B:
	s_add_i32 s33, s33, 8
	s_cmp_ge_u32 s33, s1
	s_cbranch_scc1 .Ldp_B_last
	ds_read_b32 v115, v146
	ds_read_b32 v116, v147
	s_waitcnt lgkmcnt(1)
	v_lshlrev_b32_e32 v115, 10, v115
	v_and_b32_e32 v196, 0x3fffc00, v115
	s_waitcnt lgkmcnt(0)
	v_lshlrev_b32_e32 v115, 10, v116
	v_lshl_add_u64 v[128:129], v[64:65], 0, v[196:197]
	v_and_b32_e32 v196, 0x3fffc00, v115
	v_lshl_add_u64 v[144:145], v[64:65], 0, v[196:197]
	global_load_dwordx4 v[116:119], v[128:129], off
	global_load_dwordx4 v[120:123], v[128:129], off offset:256
	global_load_dwordx4 v[124:127], v[128:129], off offset:512
	s_nop 0
	global_load_dwordx4 v[128:131], v[128:129], off offset:768
	s_nop 0
	global_load_dwordx4 v[132:135], v[144:145], off
	global_load_dwordx4 v[136:139], v[144:145], off offset:256
	global_load_dwordx4 v[140:143], v[144:145], off offset:512
	s_nop 0
	global_load_dwordx4 v[144:147], v[144:145], off offset:768
	s_waitcnt vmcnt(8)
	s_branch .Ldp_B_comp

; DI void expert_dots(const Params& p, int nrows, char* smem) {
;     ...
;   auto dot_row = [&](const int4 (&uu)[4], const f2 (&hf)[32]) {
;     const int uw[16] = {uu[0].x, uu[0].y, uu[0].z, uu[0].w, uu[1].x, uu[1].y, uu[1].z, uu[1].w,
;                         uu[2].x, uu[2].y, uu[2].z, uu[2].w, uu[3].x, uu[3].y, uu[3].z, uu[3].w};
;     f2 acc = {0.f, 0.f}, acc2 = {0.f, 0.f};
; #pragma unroll
;     for (int j = 0; j < 16; j++) {
;       acc = __builtin_elementwise_fma(__builtin_amdgcn_cvt_pk_f32_fp8(uw[j], false), hf[2 * j], acc);
;       acc2 = __builtin_elementwise_fma(__builtin_amdgcn_cvt_pk_f32_fp8(uw[j], true), hf[2 * j + 1], acc2);
;     }
;     return row16_sum((acc.x + acc.y) + (acc2.x + acc2.y));
;   };
.Ldp_B_comp:
	v_cmp_eq_u32_e32 vcc, 0, v114
	s_nop 0
	v_cvt_pk_f32_fp8_sdwa v[190:191], v156 src0_sel:WORD_1
	v_cvt_pk_f32_fp8_e32 v[188:189], v156
	v_cvt_pk_f32_fp8_e32 v[192:193], v157
	v_cvt_pk_f32_fp8_sdwa v[156:157], v157 src0_sel:WORD_1
	v_pk_fma_f32 v[190:191], v[190:191], v[48:49], 0 op_sel_hi:[1,1,0]
	v_pk_fma_f32 v[188:189], v[188:189], v[72:73], 0 op_sel_hi:[1,1,0]
	v_pk_fma_f32 v[156:157], v[156:157], v[50:51], v[190:191]
	v_cvt_pk_f32_fp8_e32 v[190:191], v158
	v_pk_fma_f32 v[188:189], v[192:193], v[74:75], v[188:189]
	s_nop 0
	v_pk_fma_f32 v[188:189], v[190:191], v[76:77], v[188:189]
	v_cvt_pk_f32_fp8_sdwa v[190:191], v158 src0_sel:WORD_1
	v_pk_fma_f32 v[156:157], v[190:191], v[32:33], v[156:157]
	v_cvt_pk_f32_fp8_e32 v[190:191], v159
	v_cvt_pk_f32_fp8_sdwa v[158:159], v159 src0_sel:WORD_1
	v_pk_fma_f32 v[188:189], v[190:191], v[78:79], v[188:189]
	v_pk_fma_f32 v[156:157], v[158:159], v[34:35], v[156:157]
	s_nop 0
	v_cvt_pk_f32_fp8_e32 v[158:159], v160
	v_pk_fma_f32 v[158:159], v[158:159], v[80:81], v[188:189]
	v_cvt_pk_f32_fp8_sdwa v[188:189], v160 src0_sel:WORD_1
	v_pk_fma_f32 v[156:157], v[188:189], v[52:53], v[156:157]
	v_cvt_pk_f32_fp8_e32 v[188:189], v161
	v_cvt_pk_f32_fp8_sdwa v[160:161], v161 src0_sel:WORD_1
	v_pk_fma_f32 v[158:159], v[188:189], v[82:83], v[158:159]
	v_pk_fma_f32 v[156:157], v[160:161], v[54:55], v[156:157]
	v_cvt_pk_f32_fp8_e32 v[160:161], v162
	v_pk_fma_f32 v[158:159], v[160:161], v[84:85], v[158:159]
	v_cvt_pk_f32_fp8_sdwa v[160:161], v162 src0_sel:WORD_1
	v_pk_fma_f32 v[156:157], v[160:161], v[36:37], v[156:157]
	v_cvt_pk_f32_fp8_e32 v[160:161], v163
	v_pk_fma_f32 v[158:159], v[160:161], v[86:87], v[158:159]
	v_cvt_pk_f32_fp8_sdwa v[160:161], v163 src0_sel:WORD_1
	v_pk_fma_f32 v[156:157], v[160:161], v[38:39], v[156:157]
	s_nop 0
	v_cvt_pk_f32_fp8_e32 v[160:161], v164
	v_pk_fma_f32 v[158:159], v[160:161], v[88:89], v[158:159]
	v_cvt_pk_f32_fp8_sdwa v[160:161], v164 src0_sel:WORD_1
	v_pk_fma_f32 v[156:157], v[160:161], v[56:57], v[156:157]
	v_cvt_pk_f32_fp8_e32 v[160:161], v165
	v_pk_fma_f32 v[158:159], v[160:161], v[90:91], v[158:159]
	v_cvt_pk_f32_fp8_sdwa v[160:161], v165 src0_sel:WORD_1
	v_pk_fma_f32 v[156:157], v[160:161], v[58:59], v[156:157]
	v_cvt_pk_f32_fp8_e32 v[160:161], v166
	v_pk_fma_f32 v[158:159], v[160:161], v[92:93], v[158:159]
	v_cvt_pk_f32_fp8_sdwa v[160:161], v166 src0_sel:WORD_1
	v_pk_fma_f32 v[156:157], v[160:161], v[40:41], v[156:157]
	v_cvt_pk_f32_fp8_e32 v[160:161], v167
	v_pk_fma_f32 v[158:159], v[160:161], v[94:95], v[158:159]
	v_cvt_pk_f32_fp8_sdwa v[160:161], v167 src0_sel:WORD_1
	v_pk_fma_f32 v[156:157], v[160:161], v[42:43], v[156:157]
	s_nop 0
	v_cvt_pk_f32_fp8_e32 v[160:161], v168
	v_pk_fma_f32 v[158:159], v[160:161], v[96:97], v[158:159]
	v_cvt_pk_f32_fp8_sdwa v[160:161], v168 src0_sel:WORD_1
	v_pk_fma_f32 v[156:157], v[160:161], v[60:61], v[156:157]
	v_cvt_pk_f32_fp8_e32 v[160:161], v169
	v_pk_fma_f32 v[158:159], v[160:161], v[98:99], v[158:159]
	v_cvt_pk_f32_fp8_sdwa v[160:161], v169 src0_sel:WORD_1
	v_pk_fma_f32 v[156:157], v[160:161], v[62:63], v[156:157]
	v_cvt_pk_f32_fp8_e32 v[160:161], v170
	v_pk_fma_f32 v[158:159], v[160:161], v[100:101], v[158:159]
	v_cvt_pk_f32_fp8_sdwa v[160:161], v170 src0_sel:WORD_1
	v_pk_fma_f32 v[156:157], v[160:161], v[44:45], v[156:157]
	v_cvt_pk_f32_fp8_e32 v[160:161], v171
	v_pk_fma_f32 v[158:159], v[160:161], v[102:103], v[158:159]
	v_cvt_pk_f32_fp8_sdwa v[160:161], v171 src0_sel:WORD_1
	v_pk_fma_f32 v[156:157], v[160:161], v[46:47], v[156:157]
	v_mov_b32_e32 v160, v158
	v_mov_b32_e32 v161, v156
	v_mov_b32_e32 v156, v159
	v_pk_add_f32 v[156:157], v[160:161], v[156:157]
	s_nop 0
	v_cvt_pk_f32_fp8_e32 v[160:161], v173
	v_add_f32_e32 v155, v156, v157
	v_cvt_pk_f32_fp8_e32 v[156:157], v172
	v_cvt_pk_f32_fp8_sdwa v[158:159], v172 src0_sel:WORD_1
	v_add_f32_dpp v155, v155, v155 row_ror:8 row_mask:0xf bank_mask:0xf bound_ctrl:1
	v_pk_fma_f32 v[156:157], v[156:157], v[72:73], 0 op_sel_hi:[1,1,0]
	s_nop 0
	v_pk_fma_f32 v[156:157], v[160:161], v[74:75], v[156:157]
	v_cvt_pk_f32_fp8_sdwa v[160:161], v173 src0_sel:WORD_1
	v_pk_fma_f32 v[158:159], v[158:159], v[48:49], 0 op_sel_hi:[1,1,0]
	v_add_f32_dpp v155, v155, v155 row_ror:4 row_mask:0xf bank_mask:0xf bound_ctrl:1
; DI void expert_dots(const Params& p, int nrows, char* smem) {
;     ...
;   auto dot_row = [&](const int4 (&uu)[4], const f2 (&hf)[32]) {
;     const int uw[16] = {uu[0].x, uu[0].y, uu[0].z, uu[0].w, uu[1].x, uu[1].y, uu[1].z, uu[1].w,
;                         uu[2].x, uu[2].y, uu[2].z, uu[2].w, uu[3].x, uu[3].y, uu[3].z, uu[3].w};
;     f2 acc = {0.f, 0.f}, acc2 = {0.f, 0.f};
; #pragma unroll
;     for (int j = 0; j < 16; j++) {
;       acc = __builtin_elementwise_fma(__builtin_amdgcn_cvt_pk_f32_fp8(uw[j], false), hf[2 * j], acc);
;       acc2 = __builtin_elementwise_fma(__builtin_amdgcn_cvt_pk_f32_fp8(uw[j], true), hf[2 * j + 1], acc2);
;     }
;     return row16_sum((acc.x + acc.y) + (acc2.x + acc2.y));
;   };
;     ...
;       for (int base = cb; base < nend; base += 8) {
;         const int k0 = base + g, k1 = base + 4 + g;
;         const u32 ent0 = list[min(k0, n - 1)], ent1 = list[min(k1, n - 1)];
;         const unsigned char* ur0 = PU + (size_t)(ent0 & 0xffffu) * D;
;         const unsigned char* ur1 = PU + (size_t)(ent1 & 0xffffu) * D;
;         int4 ua[4], ub[4];
;         ua[0] = *(const int4*)(ur0); ua[1] = *(const int4*)(ur0 + 256); ua[2] = *(const int4*)(ur0 + 512); ua[3] = *(const int4*)(ur0 + 768);
;         ub[0] = *(const int4*)(ur1); ub[1] = *(const int4*)(ur1 + 256); ub[2] = *(const int4*)(ur1 + 512); ub[3] = *(const int4*)(ur1 + 768);
;         const float d0 = dot_row(ua, hf);
;         const float d1 = dot_row(ub, hf);
;         const int it0 = (base - cb) >> 2;
;         dk = (s == it0) ? d0 : dk;
;         dk = (s == it0 + 1) ? d1 : dk;
;       }
	v_pk_fma_f32 v[158:159], v[160:161], v[50:51], v[158:159]
	v_cvt_pk_f32_fp8_e32 v[160:161], v174
	v_add_f32_dpp v155, v155, v155 row_ror:2 row_mask:0xf bank_mask:0xf bound_ctrl:1
	v_pk_fma_f32 v[156:157], v[160:161], v[76:77], v[156:157]
	v_cvt_pk_f32_fp8_sdwa v[160:161], v174 src0_sel:WORD_1
	v_add_f32_dpp v155, v155, v155 row_ror:1 row_mask:0xf bank_mask:0xf bound_ctrl:1
	v_cndmask_b32_e32 v113, v113, v155, vcc
	v_cmp_eq_u32_e32 vcc, 1, v114
	v_pk_fma_f32 v[158:159], v[160:161], v[32:33], v[158:159]
	v_cvt_pk_f32_fp8_e32 v[160:161], v175
	v_add_u32_e32 v114, -2, v114
	v_pk_fma_f32 v[156:157], v[160:161], v[78:79], v[156:157]
	v_cvt_pk_f32_fp8_sdwa v[160:161], v175 src0_sel:WORD_1
	v_pk_fma_f32 v[158:159], v[160:161], v[34:35], v[158:159]
	s_nop 0
	v_cvt_pk_f32_fp8_e32 v[160:161], v176
	v_pk_fma_f32 v[156:157], v[160:161], v[80:81], v[156:157]
	v_cvt_pk_f32_fp8_sdwa v[160:161], v176 src0_sel:WORD_1
	v_pk_fma_f32 v[158:159], v[160:161], v[52:53], v[158:159]
	v_cvt_pk_f32_fp8_e32 v[160:161], v177
	v_pk_fma_f32 v[156:157], v[160:161], v[82:83], v[156:157]
	v_cvt_pk_f32_fp8_sdwa v[160:161], v177 src0_sel:WORD_1
	v_pk_fma_f32 v[158:159], v[160:161], v[54:55], v[158:159]
	v_cvt_pk_f32_fp8_e32 v[160:161], v178
	v_pk_fma_f32 v[156:157], v[160:161], v[84:85], v[156:157]
	v_cvt_pk_f32_fp8_sdwa v[160:161], v178 src0_sel:WORD_1
	v_pk_fma_f32 v[158:159], v[160:161], v[36:37], v[158:159]
	v_cvt_pk_f32_fp8_e32 v[160:161], v179
	v_pk_fma_f32 v[156:157], v[160:161], v[86:87], v[156:157]
	v_cvt_pk_f32_fp8_sdwa v[160:161], v179 src0_sel:WORD_1
	v_pk_fma_f32 v[158:159], v[160:161], v[38:39], v[158:159]
	s_nop 0
	v_cvt_pk_f32_fp8_e32 v[160:161], v180
	v_pk_fma_f32 v[156:157], v[160:161], v[88:89], v[156:157]
	v_cvt_pk_f32_fp8_sdwa v[160:161], v180 src0_sel:WORD_1
	v_pk_fma_f32 v[158:159], v[160:161], v[56:57], v[158:159]
	v_cvt_pk_f32_fp8_e32 v[160:161], v181
	v_pk_fma_f32 v[156:157], v[160:161], v[90:91], v[156:157]
	v_cvt_pk_f32_fp8_sdwa v[160:161], v181 src0_sel:WORD_1
	v_pk_fma_f32 v[158:159], v[160:161], v[58:59], v[158:159]
	v_cvt_pk_f32_fp8_e32 v[160:161], v182
	v_pk_fma_f32 v[156:157], v[160:161], v[92:93], v[156:157]
	v_cvt_pk_f32_fp8_sdwa v[160:161], v182 src0_sel:WORD_1
	v_pk_fma_f32 v[158:159], v[160:161], v[40:41], v[158:159]
	v_cvt_pk_f32_fp8_e32 v[160:161], v183
	v_pk_fma_f32 v[156:157], v[160:161], v[94:95], v[156:157]
	v_cvt_pk_f32_fp8_sdwa v[160:161], v183 src0_sel:WORD_1
	v_pk_fma_f32 v[158:159], v[160:161], v[42:43], v[158:159]
	s_nop 0
	v_cvt_pk_f32_fp8_e32 v[160:161], v184
	v_pk_fma_f32 v[156:157], v[160:161], v[96:97], v[156:157]
	v_cvt_pk_f32_fp8_sdwa v[160:161], v184 src0_sel:WORD_1
	v_pk_fma_f32 v[158:159], v[160:161], v[60:61], v[158:159]
	v_cvt_pk_f32_fp8_e32 v[160:161], v185
	v_pk_fma_f32 v[156:157], v[160:161], v[98:99], v[156:157]
	v_cvt_pk_f32_fp8_sdwa v[160:161], v185 src0_sel:WORD_1
	v_pk_fma_f32 v[158:159], v[160:161], v[62:63], v[158:159]
	v_cvt_pk_f32_fp8_e32 v[160:161], v186
	v_pk_fma_f32 v[156:157], v[160:161], v[100:101], v[156:157]
	v_cvt_pk_f32_fp8_sdwa v[160:161], v186 src0_sel:WORD_1
	v_pk_fma_f32 v[158:159], v[160:161], v[44:45], v[158:159]
	v_cvt_pk_f32_fp8_e32 v[160:161], v187
	v_pk_fma_f32 v[156:157], v[160:161], v[102:103], v[156:157]
	v_cvt_pk_f32_fp8_sdwa v[160:161], v187 src0_sel:WORD_1
	v_pk_fma_f32 v[158:159], v[160:161], v[46:47], v[158:159]
	v_mov_b32_e32 v160, v156
	v_mov_b32_e32 v161, v158
	v_mov_b32_e32 v158, v157
	v_pk_add_f32 v[156:157], v[160:161], v[158:159]
	s_nop 0
	v_add_f32_e32 v156, v156, v157
	v_add3_u32 v186, s33, v106, 8
	v_add_u32_e32 v187, 4, v186
	v_add_f32_dpp v156, v156, v156 row_ror:8 row_mask:0xf bank_mask:0xf bound_ctrl:1
	v_min_i32_e32 v186, s5, v186
	v_min_i32_e32 v187, s5, v187
	v_add_f32_dpp v156, v156, v156 row_ror:4 row_mask:0xf bank_mask:0xf bound_ctrl:1
	v_lshl_add_u32 v186, v186, 2, v108
	v_lshl_add_u32 v187, v187, 2, v108
	v_add_f32_dpp v156, v156, v156 row_ror:2 row_mask:0xf bank_mask:0xf bound_ctrl:1
	s_nop 1
	v_add_f32_dpp v156, v156, v156 row_ror:1 row_mask:0xf bank_mask:0xf bound_ctrl:1
	v_cndmask_b32_e32 v113, v113, v156, vcc
	s_cbranch_scc1 .Ldp_done
	s_add_i32 s33, s33, 8
	s_cmp_ge_u32 s33, s1
	s_cbranch_scc1 .Ldp_A_last
	s_branch .Ldp_A2
